# attn: K/V fragment LDS reads issued 3-8 MFMA slots ahead (freed epilogue offset regs), rebalanced softmax VALU
# baseline (speedup 1.0000x reference)
; __device__ __forceinline__ unsigned cvtpk(float lo, float hi) { f32x2_t v = {lo, hi}; bf16x2_t b = __builtin_convertvector(v, bf16x2_t); return __builtin_bit_cast(unsigned, b); }
; __device__ __forceinline__ int crow(int r, int hi) { return (r & 3) + 8 * (r >> 2) + 4 * hi; }
; __device__ __forceinline__ void attn_unit(const Ctx& c, int bh, int qb, const bf16_t* Q, const bf16_t* Kb, const bf16_t* Vb, bf16_t* O) {
;     ...
;     lsum += __int_as_float(__builtin_amdgcn_ds_bpermute((lane ^ 32) * 4, __float_as_int(lsum)));
;     if (hi == 0) wsf[r32] = 1.0f / lsum;
;     asm volatile("" ::: "memory");
;     bf16_t* op = O + (rowbase + q0 + wid * 32) * 1024 + h * 64 + r32;
; #pragma unroll
;     for (int r = 0; r < 16; ++r) { const int qq = crow(r, hi); const float rl = wsf[qq];
;         op[(size_t)qq * 1024] = (bf16_t)(cvtpk(o[0][r] * rl, 0.f) & 0xffffu); op[(size_t)qq * 1024 + 32] = (bf16_t)(cvtpk(o[1][r] * rl, 0.f) & 0xffffu); }
;     asm volatile("" ::: "memory");
.LBB0_276:
	s_or_b64 exec, exec, s[6:7]
	v_or_b32_e32 v160, 0x800, v158
	v_mov_b32_e32 v161, v211
	v_or_b32_e32 v162, 0x1000, v158
	v_mov_b32_e32 v163, v211
	v_or_b32_e32 v164, 0x1800, v158
	v_mov_b32_e32 v165, v211
	v_or_b32_e32 v166, 0x4000, v158
	v_mov_b32_e32 v167, v211
	v_or_b32_e32 v168, 0x4800, v158
	v_mov_b32_e32 v169, v211
	v_or_b32_e32 v170, 0x5000, v158
	v_mov_b32_e32 v171, v211
	v_or_b32_e32 v172, 0x5800, v158
	v_mov_b32_e32 v173, v211
	v_or_b32_e32 v174, 0x8000, v158
	v_mov_b32_e32 v175, v211
	v_or_b32_e32 v176, 0x8800, v158
	v_mov_b32_e32 v177, v211
	v_or_b32_e32 v178, 0x9000, v158
	v_mov_b32_e32 v179, v211
	v_or_b32_e32 v180, 0x9800, v158
	v_mov_b32_e32 v181, v211
	v_or_b32_e32 v182, 0xc000, v158
	v_mov_b32_e32 v183, v211
	v_or_b32_e32 v184, 0xc800, v158
	v_mov_b32_e32 v185, v211
	v_or_b32_e32 v186, 0xd000, v158
	v_mov_b32_e32 v187, v211
	s_lshl_b64 s[6:7], s[46:47], 11
	s_waitcnt lgkmcnt(0)
	ds_read_b128 v[32:35], v221
	ds_read_b128 v[36:39], v221 offset:32
	s_add_u32 s5, s76, s6
	s_addc_u32 s6, s77, s7
	s_lshl_b32 s4, s4, 1
	s_add_u32 s4, s5, s4
	s_addc_u32 s5, s6, 0
	v_mov_b32_e32 v193, v211
	v_lshl_add_u64 v[40:41], s[4:5], 0, v[192:193]
	s_waitcnt lgkmcnt(1)
	v_mul_f32_e32 v0, v0, v32
	v_mul_f32_e32 v16, v16, v32
	v_lshl_add_u64 v[42:43], v[40:41], 0, v[158:159]
	v_cvt_pk_bf16_f32 v0, v0, s0
	v_cvt_pk_bf16_f32 v16, v16, s0
	global_store_short v[42:43], v0, off offset:64
	v_mul_f32_e32 v0, v17, v33
	global_store_short v[42:43], v16, off
	v_cvt_pk_bf16_f32 v0, v0, s0
	v_lshl_add_u64 v[16:17], v[40:41], 0, v[160:161]
	global_store_short v[16:17], v0, off
	v_mul_f32_e32 v0, v1, v33
	v_cvt_pk_bf16_f32 v0, v0, s0
	global_store_short v[16:17], v0, off offset:64
	v_mul_f32_e32 v0, v18, v34
	v_mul_f32_e32 v2, v2, v34
	v_cvt_pk_bf16_f32 v16, v0, s0
	v_lshl_add_u64 v[0:1], v[40:41], 0, v[162:163]
	v_cvt_pk_bf16_f32 v2, v2, s0
	global_store_short v[0:1], v16, off
	global_store_short v[0:1], v2, off offset:64
	v_mul_f32_e32 v0, v19, v35
	v_cvt_pk_bf16_f32 v2, v0, s0
	v_lshl_add_u64 v[0:1], v[40:41], 0, v[164:165]
	global_store_short v[0:1], v2, off
	v_mul_f32_e32 v2, v3, v35
	v_cvt_pk_bf16_f32 v2, v2, s0
	global_store_short v[0:1], v2, off offset:64
	s_waitcnt lgkmcnt(0)
	v_mul_f32_e32 v0, v20, v36
	v_cvt_pk_bf16_f32 v2, v0, s0
	v_lshl_add_u64 v[0:1], v[40:41], 0, v[166:167]
	global_store_short v[0:1], v2, off
	v_mul_f32_e32 v2, v4, v36
	v_cvt_pk_bf16_f32 v2, v2, s0
	global_store_short v[0:1], v2, off offset:64
	v_mul_f32_e32 v0, v21, v37
	v_cvt_pk_bf16_f32 v2, v0, s0
	v_lshl_add_u64 v[0:1], v[40:41], 0, v[168:169]
	global_store_short v[0:1], v2, off
	v_mul_f32_e32 v2, v5, v37
	v_cvt_pk_bf16_f32 v2, v2, s0
	global_store_short v[0:1], v2, off offset:64
	v_mul_f32_e32 v0, v22, v38
	v_cvt_pk_bf16_f32 v2, v0, s0
	v_lshl_add_u64 v[0:1], v[40:41], 0, v[170:171]
	global_store_short v[0:1], v2, off
	v_mul_f32_e32 v2, v6, v38
	v_cvt_pk_bf16_f32 v2, v2, s0
	global_store_short v[0:1], v2, off offset:64
	v_mul_f32_e32 v0, v23, v39
	v_cvt_pk_bf16_f32 v0, v0, s0
	v_lshl_add_u64 v[4:5], v[40:41], 0, v[172:173]
	global_store_short v[4:5], v0, off
	ds_read_b128 v[0:3], v221 offset:64
	v_mul_f32_e32 v6, v7, v39
	v_cvt_pk_bf16_f32 v6, v6, s0
	global_store_short v[4:5], v6, off offset:64
	ds_read_b128 v[4:7], v221 offset:96
	s_waitcnt lgkmcnt(1)
	v_mul_f32_e32 v16, v24, v0
	v_mul_f32_e32 v0, v8, v0
	v_cvt_pk_bf16_f32 v18, v16, s0
	v_lshl_add_u64 v[16:17], v[40:41], 0, v[174:175]
	v_cvt_pk_bf16_f32 v0, v0, s0
	global_store_short v[16:17], v0, off offset:64
	v_mul_f32_e32 v0, v25, v1
	global_store_short v[16:17], v18, off
	v_cvt_pk_bf16_f32 v0, v0, s0
	v_lshl_add_u64 v[16:17], v[40:41], 0, v[176:177]
	global_store_short v[16:17], v0, off
	v_mul_f32_e32 v0, v9, v1
	v_cvt_pk_bf16_f32 v0, v0, s0
	global_store_short v[16:17], v0, off offset:64
	v_mul_f32_e32 v0, v26, v2
	v_mul_f32_e32 v2, v10, v2
	v_cvt_pk_bf16_f32 v8, v0, s0
	v_lshl_add_u64 v[0:1], v[40:41], 0, v[178:179]
	v_cvt_pk_bf16_f32 v2, v2, s0
	global_store_short v[0:1], v8, off
	global_store_short v[0:1], v2, off offset:64
	v_mul_f32_e32 v0, v27, v3
	v_cvt_pk_bf16_f32 v2, v0, s0
	v_lshl_add_u64 v[0:1], v[40:41], 0, v[180:181]
	global_store_short v[0:1], v2, off
	v_mul_f32_e32 v2, v11, v3
	v_cvt_pk_bf16_f32 v2, v2, s0
	global_store_short v[0:1], v2, off offset:64
	s_waitcnt lgkmcnt(0)
	v_mul_f32_e32 v0, v28, v4
	v_cvt_pk_bf16_f32 v2, v0, s0
	v_lshl_add_u64 v[0:1], v[40:41], 0, v[182:183]
	global_store_short v[0:1], v2, off
	v_mul_f32_e32 v2, v12, v4
	v_cvt_pk_bf16_f32 v2, v2, s0
	global_store_short v[0:1], v2, off offset:64
	v_mul_f32_e32 v0, v29, v5
	v_cvt_pk_bf16_f32 v2, v0, s0
	v_lshl_add_u64 v[0:1], v[40:41], 0, v[184:185]
	global_store_short v[0:1], v2, off
	v_mul_f32_e32 v2, v13, v5
	v_cvt_pk_bf16_f32 v2, v2, s0
	global_store_short v[0:1], v2, off offset:64
	v_mul_f32_e32 v0, v30, v6
	v_cvt_pk_bf16_f32 v2, v0, s0
	v_lshl_add_u64 v[0:1], v[40:41], 0, v[186:187]
	global_store_short v[0:1], v2, off
	v_mul_f32_e32 v2, v14, v6
	v_cvt_pk_bf16_f32 v2, v2, s0
	global_store_short v[0:1], v2, off offset:64
	v_mul_f32_e32 v0, v31, v7
	v_cvt_pk_bf16_f32 v2, v0, s0
	v_lshl_add_u64 v[0:1], v[40:41], 0, v[188:189]
	global_store_short v[0:1], v2, off
	v_mul_f32_e32 v2, v15, v7
	v_cvt_pk_bf16_f32 v2, v2, s0
	global_store_short v[0:1], v2, off offset:64
	s_add_i32 s3, s3, s15
	s_cmpk_gt_i32 s3, 0x3ff
	s_cbranch_scc1 .LBB0_314

.LBB0_290:
	s_add_i32 s27, s12, 0
	s_mov_b32 s25, s11
	s_mov_b32 s11, s56
	v_add_u32_e32 v213, s25, v203
	v_add_u32_e32 v214, v213, v204
	ds_read_b128 v[160:163], v214
	ds_read_b128 v[164:167], v214 offset:512
	v_add_u32_e32 v214, v213, v205
	ds_read_b128 v[168:171], v214 offset:2048
	ds_read_b128 v[172:175], v214 offset:2560
	v_add_u32_e32 v214, v213, v206
	ds_read_b128 v[176:179], v214 offset:4096
	ds_read_b128 v[180:183], v214 offset:4608
	v_add_u32_e32 v212, s27, v97
	s_waitcnt vmcnt(5)
	ds_write_b128 v212, v[122:125]
	s_and_saveexec_b64 s[6:7], s[42:43]
	s_cbranch_execz .LBB0_292
	v_add_u32_e32 v122, s27, v147
	s_waitcnt vmcnt(4)
	ds_write_b128 v122, v[126:129]

.LBB0_299:
	v_add_u32_e32 v193, s25, v203
	s_waitcnt lgkmcnt(7)
	v_mfma_f32_32x32x16_bf16 v[64:79], v[160:163], v[98:101], 0
	v_add_u32_e32 v214, v193, v207
	ds_read_b128 v[224:227], v214 offset:6144
	ds_read_b128 v[228:231], v214 offset:6656
	v_sub_f32_e32 v32, v32, v222
	v_sub_f32_e32 v33, v33, v222
	v_exp_f32_e32 v32, v32
	v_exp_f32_e32 v33, v33
	s_waitcnt lgkmcnt(8)
	v_mfma_f32_32x32x16_bf16 v[80:95], v[164:167], v[98:101], 0
	v_add_u32_e32 v214, v193, v208
	ds_read_b128 v[242:245], v214 offset:8192
	ds_read_b128 v[246:249], v214 offset:8704
	v_sub_f32_e32 v34, v34, v222
	v_sub_f32_e32 v35, v35, v222
	v_exp_f32_e32 v34, v34
	v_exp_f32_e32 v35, v35
	s_waitcnt lgkmcnt(9)
	v_mfma_f32_32x32x16_bf16 v[64:79], v[168:171], v[102:105], v[64:79]
	v_add_u32_e32 v214, v193, v209
	ds_read_b128 v[160:163], v214 offset:10240
	ds_read_b128 v[164:167], v214 offset:10752
	v_sub_f32_e32 v36, v36, v222
	v_sub_f32_e32 v37, v37, v222
	v_exp_f32_e32 v36, v36
	v_exp_f32_e32 v37, v37
	s_waitcnt lgkmcnt(10)
	v_mfma_f32_32x32x16_bf16 v[80:95], v[172:175], v[102:105], v[80:95]
	v_add_u32_e32 v213, s11, v218
	v_sub_f32_e32 v38, v38, v222
	v_sub_f32_e32 v39, v39, v222
	v_exp_f32_e32 v38, v38
	v_exp_f32_e32 v39, v39
	s_waitcnt lgkmcnt(9)
	v_mfma_f32_32x32x16_bf16 v[64:79], v[176:179], v[106:109], v[64:79]
	ds_read_b64_tr_b16 v[168:169], v213 offset:12288
	ds_read_b64_tr_b16 v[170:171], v213 offset:13824
	v_sub_f32_e32 v40, v40, v222
	v_sub_f32_e32 v41, v41, v222
	v_exp_f32_e32 v40, v40
	v_exp_f32_e32 v41, v41
	s_waitcnt lgkmcnt(10)
	v_mfma_f32_32x32x16_bf16 v[80:95], v[180:183], v[106:109], v[80:95]
	ds_read_b64_tr_b16 v[172:173], v213 offset:12352
	ds_read_b64_tr_b16 v[174:175], v213 offset:13888
	v_sub_f32_e32 v42, v42, v222
	v_sub_f32_e32 v43, v43, v222
	v_exp_f32_e32 v42, v42
	v_exp_f32_e32 v43, v43
	s_waitcnt lgkmcnt(9)
	v_mfma_f32_32x32x16_bf16 v[64:79], v[224:227], v[110:113], v[64:79]
	ds_read_b64_tr_b16 v[176:177], v213 offset:15360
	ds_read_b64_tr_b16 v[178:179], v213 offset:16896
	v_sub_f32_e32 v44, v44, v222
	v_sub_f32_e32 v45, v45, v222
	v_exp_f32_e32 v44, v44
	v_exp_f32_e32 v45, v45
	s_waitcnt lgkmcnt(10)
	v_mfma_f32_32x32x16_bf16 v[80:95], v[228:231], v[110:113], v[80:95]
	ds_read_b64_tr_b16 v[180:181], v213 offset:15424
	ds_read_b64_tr_b16 v[182:183], v213 offset:16960
	v_sub_f32_e32 v46, v46, v222
	v_sub_f32_e32 v47, v47, v222
	v_exp_f32_e32 v46, v46
	v_exp_f32_e32 v47, v47
	s_waitcnt lgkmcnt(11)
	v_mfma_f32_32x32x16_bf16 v[64:79], v[242:245], v[114:117], v[64:79]
	ds_read_b64_tr_b16 v[184:185], v213 offset:18432
	ds_read_b64_tr_b16 v[186:187], v213 offset:19968
	v_cvt_pk_bf16_f32 v242, v32, v33
	v_cvt_pk_bf16_f32 v243, v34, v35
	v_sub_f32_e32 v48, v48, v222
	v_sub_f32_e32 v49, v49, v222
	v_exp_f32_e32 v48, v48
	v_exp_f32_e32 v49, v49
	s_waitcnt lgkmcnt(12)
	v_mfma_f32_32x32x16_bf16 v[80:95], v[246:249], v[114:117], v[80:95]
	ds_read_b64_tr_b16 v[250:251], v213 offset:18496
	ds_read_b64_tr_b16 v[252:253], v213 offset:20032
	v_cvt_pk_bf16_f32 v244, v36, v37
	v_cvt_pk_bf16_f32 v245, v38, v39
	v_sub_f32_e32 v50, v50, v222
	v_sub_f32_e32 v51, v51, v222
	v_exp_f32_e32 v50, v50
	v_exp_f32_e32 v51, v51
	s_waitcnt lgkmcnt(13)
	v_mfma_f32_32x32x16_bf16 v[64:79], v[160:163], v[118:121], v[64:79]
	ds_read_b64_tr_b16 v[228:229], v213 offset:21504
	ds_read_b64_tr_b16 v[230:231], v213 offset:23040
	v_cvt_pk_bf16_f32 v224, v40, v41
	v_cvt_pk_bf16_f32 v225, v42, v43
	v_sub_f32_e32 v52, v52, v222
	v_sub_f32_e32 v53, v53, v222
	v_exp_f32_e32 v52, v52
	v_exp_f32_e32 v53, v53
	s_waitcnt lgkmcnt(14)
	v_mfma_f32_32x32x16_bf16 v[80:95], v[164:167], v[118:121], v[80:95]
	ds_read_b64_tr_b16 v[164:165], v213 offset:21568
	ds_read_b64_tr_b16 v[166:167], v213 offset:23104
	v_cvt_pk_bf16_f32 v226, v44, v45
	v_cvt_pk_bf16_f32 v227, v46, v47
	v_sub_f32_e32 v54, v54, v222
	v_sub_f32_e32 v55, v55, v222
	v_exp_f32_e32 v54, v54
	v_exp_f32_e32 v55, v55
	s_waitcnt lgkmcnt(14)
	v_mfma_f32_32x32x16_bf16 v[16:31], v[242:245], v[168:171], v[16:31]
	v_cvt_pk_bf16_f32 v246, v48, v49
	v_sub_f32_e32 v56, v56, v222
	v_sub_f32_e32 v57, v57, v222
	v_exp_f32_e32 v56, v56
	v_exp_f32_e32 v57, v57
	v_add_f32_e32 v216, v32, v34
	v_add_f32_e32 v217, v33, v35
	s_waitcnt lgkmcnt(12)
	v_mfma_f32_32x32x16_bf16 v[0:15], v[242:245], v[172:175], v[0:15]
	v_cvt_pk_bf16_f32 v247, v50, v51
	v_sub_f32_e32 v58, v58, v222
	v_sub_f32_e32 v59, v59, v222
	v_exp_f32_e32 v58, v58
	v_exp_f32_e32 v59, v59
	v_add_f32_e32 v216, v216, v36
	v_add_f32_e32 v217, v217, v37
	s_waitcnt lgkmcnt(10)
	v_mfma_f32_32x32x16_bf16 v[16:31], v[224:227], v[176:179], v[16:31]
	v_cvt_pk_bf16_f32 v248, v52, v53
	v_sub_f32_e32 v60, v60, v222
	v_sub_f32_e32 v61, v61, v222
	v_exp_f32_e32 v60, v60
	v_exp_f32_e32 v61, v61
	v_add_f32_e32 v216, v216, v38
	v_add_f32_e32 v217, v217, v39
	s_waitcnt lgkmcnt(8)
	v_mfma_f32_32x32x16_bf16 v[0:15], v[224:227], v[180:183], v[0:15]
	v_cvt_pk_bf16_f32 v249, v54, v55
	v_sub_f32_e32 v62, v62, v222
	v_sub_f32_e32 v63, v63, v222
	v_exp_f32_e32 v62, v62
	v_exp_f32_e32 v63, v63
	v_add_f32_e32 v216, v216, v40
	v_add_f32_e32 v217, v217, v41
	s_waitcnt lgkmcnt(6)
	v_mfma_f32_32x32x16_bf16 v[16:31], v[246:249], v[184:187], v[16:31]
	v_cvt_pk_bf16_f32 v242, v56, v57
	v_cvt_pk_bf16_f32 v243, v58, v59
	v_add_f32_e32 v216, v216, v42
	v_add_f32_e32 v217, v217, v43
	v_add_f32_e32 v216, v216, v44
	v_add_f32_e32 v217, v217, v45
	v_add_f32_e32 v216, v216, v46
	v_add_f32_e32 v217, v217, v47
	s_waitcnt lgkmcnt(4)
	v_mfma_f32_32x32x16_bf16 v[0:15], v[246:249], v[250:253], v[0:15]
	v_cvt_pk_bf16_f32 v244, v60, v61
	v_cvt_pk_bf16_f32 v245, v62, v63
	v_add_f32_e32 v216, v216, v48
	v_add_f32_e32 v217, v217, v49
	v_add_f32_e32 v216, v216, v50
	v_add_f32_e32 v217, v217, v51
	v_add_f32_e32 v216, v216, v52
	v_add_f32_e32 v217, v217, v53
	s_waitcnt lgkmcnt(2)
	v_mfma_f32_32x32x16_bf16 v[16:31], v[242:245], v[228:231], v[16:31]
	v_add_f32_e32 v216, v216, v54
	v_add_f32_e32 v217, v217, v55
	v_add_f32_e32 v216, v216, v56
	v_add_f32_e32 v217, v217, v57
	v_add_f32_e32 v216, v216, v58
	v_add_f32_e32 v217, v217, v59
	s_waitcnt lgkmcnt(0)
	v_mfma_f32_32x32x16_bf16 v[0:15], v[242:245], v[164:167], v[0:15]
	v_add_f32_e32 v216, v216, v60
	v_add_f32_e32 v217, v217, v61
	v_add_f32_e32 v216, v216, v62
	v_add_f32_e32 v217, v217, v63
	v_add_f32_e32 v216, v216, v217
	v_add_f32_e32 v191, v191, v216
.LBB0_300:
	s_waitcnt lgkmcnt(0)
	s_barrier
	v_add3_u32 v213, s27, v201, v202
	v_add_u32_e32 v214, v213, v204
	ds_read_b128 v[160:163], v214
	ds_read_b128 v[164:167], v214 offset:512
	v_add_u32_e32 v214, v213, v205
	ds_read_b128 v[168:171], v214 offset:2048
	ds_read_b128 v[172:175], v214 offset:2560
	v_add_u32_e32 v214, v213, v206
	ds_read_b128 v[176:179], v214 offset:4096
	ds_read_b128 v[180:183], v214 offset:4608
	s_add_i32 s16, s11, 0
	v_add_u32_e32 v193, s16, v97
	s_waitcnt vmcnt(5)
	ds_write_b128 v193, v[134:137]
	s_and_saveexec_b64 s[6:7], s[42:43]
	s_cbranch_execz .LBB0_302
	v_add_u32_e32 v134, s16, v147
	s_waitcnt vmcnt(4)
	ds_write_b128 v134, v[138:141]

.LBB0_309:
	v_add3_u32 v212, s27, v201, v202
	s_waitcnt lgkmcnt(7)
	v_mfma_f32_32x32x16_bf16 v[32:47], v[160:163], v[98:101], 0
	v_add_u32_e32 v214, v212, v207
	ds_read_b128 v[224:227], v214 offset:6144
	ds_read_b128 v[228:231], v214 offset:6656
	v_sub_f32_e32 v64, v64, v193
	v_sub_f32_e32 v65, v65, v193
	v_exp_f32_e32 v64, v64
	v_exp_f32_e32 v65, v65
	s_waitcnt lgkmcnt(8)
	v_mfma_f32_32x32x16_bf16 v[48:63], v[164:167], v[98:101], 0
	v_add_u32_e32 v214, v212, v208
	ds_read_b128 v[242:245], v214 offset:8192
	ds_read_b128 v[246:249], v214 offset:8704
	v_sub_f32_e32 v66, v66, v193
	v_sub_f32_e32 v67, v67, v193
	v_exp_f32_e32 v66, v66
	v_exp_f32_e32 v67, v67
	s_waitcnt lgkmcnt(9)
	v_mfma_f32_32x32x16_bf16 v[32:47], v[168:171], v[102:105], v[32:47]
	v_add_u32_e32 v214, v212, v209
	ds_read_b128 v[160:163], v214 offset:10240
	ds_read_b128 v[164:167], v214 offset:10752
	v_sub_f32_e32 v68, v68, v193
	v_sub_f32_e32 v69, v69, v193
	v_exp_f32_e32 v68, v68
	v_exp_f32_e32 v69, v69
	s_waitcnt lgkmcnt(10)
	v_mfma_f32_32x32x16_bf16 v[48:63], v[172:175], v[102:105], v[48:63]
	v_add_u32_e32 v213, s25, v218
	v_sub_f32_e32 v70, v70, v193
	v_sub_f32_e32 v71, v71, v193
	v_exp_f32_e32 v70, v70
	v_exp_f32_e32 v71, v71
	s_waitcnt lgkmcnt(9)
	v_mfma_f32_32x32x16_bf16 v[32:47], v[176:179], v[106:109], v[32:47]
	ds_read_b64_tr_b16 v[168:169], v213 offset:12288
	ds_read_b64_tr_b16 v[170:171], v213 offset:13824
	v_sub_f32_e32 v72, v72, v193
	v_sub_f32_e32 v73, v73, v193
	v_exp_f32_e32 v72, v72
	v_exp_f32_e32 v73, v73
	s_waitcnt lgkmcnt(10)
	v_mfma_f32_32x32x16_bf16 v[48:63], v[180:183], v[106:109], v[48:63]
	ds_read_b64_tr_b16 v[172:173], v213 offset:12352
	ds_read_b64_tr_b16 v[174:175], v213 offset:13888
	v_sub_f32_e32 v74, v74, v193
	v_sub_f32_e32 v75, v75, v193
	v_exp_f32_e32 v74, v74
	v_exp_f32_e32 v75, v75
	s_waitcnt lgkmcnt(9)
	v_mfma_f32_32x32x16_bf16 v[32:47], v[224:227], v[110:113], v[32:47]
	ds_read_b64_tr_b16 v[176:177], v213 offset:15360
	ds_read_b64_tr_b16 v[178:179], v213 offset:16896
	v_sub_f32_e32 v76, v76, v193
	v_sub_f32_e32 v77, v77, v193
	v_exp_f32_e32 v76, v76
	v_exp_f32_e32 v77, v77
	s_waitcnt lgkmcnt(10)
	v_mfma_f32_32x32x16_bf16 v[48:63], v[228:231], v[110:113], v[48:63]
	ds_read_b64_tr_b16 v[180:181], v213 offset:15424
	ds_read_b64_tr_b16 v[182:183], v213 offset:16960
	v_sub_f32_e32 v78, v78, v193
	v_sub_f32_e32 v79, v79, v193
	v_exp_f32_e32 v78, v78
	v_exp_f32_e32 v79, v79
	s_waitcnt lgkmcnt(11)
	v_mfma_f32_32x32x16_bf16 v[32:47], v[242:245], v[114:117], v[32:47]
	ds_read_b64_tr_b16 v[184:185], v213 offset:18432
	ds_read_b64_tr_b16 v[186:187], v213 offset:19968
	v_cvt_pk_bf16_f32 v242, v64, v65
	v_cvt_pk_bf16_f32 v243, v66, v67
	v_sub_f32_e32 v80, v80, v193
	v_sub_f32_e32 v81, v81, v193
	v_exp_f32_e32 v80, v80
	v_exp_f32_e32 v81, v81
	s_waitcnt lgkmcnt(12)
	v_mfma_f32_32x32x16_bf16 v[48:63], v[246:249], v[114:117], v[48:63]
	ds_read_b64_tr_b16 v[250:251], v213 offset:18496
	ds_read_b64_tr_b16 v[252:253], v213 offset:20032
	v_cvt_pk_bf16_f32 v244, v68, v69
	v_cvt_pk_bf16_f32 v245, v70, v71
	v_sub_f32_e32 v82, v82, v193
	v_sub_f32_e32 v83, v83, v193
	v_exp_f32_e32 v82, v82
	v_exp_f32_e32 v83, v83
	s_waitcnt lgkmcnt(13)
	v_mfma_f32_32x32x16_bf16 v[32:47], v[160:163], v[118:121], v[32:47]
	ds_read_b64_tr_b16 v[228:229], v213 offset:21504
	ds_read_b64_tr_b16 v[230:231], v213 offset:23040
	v_cvt_pk_bf16_f32 v224, v72, v73
	v_cvt_pk_bf16_f32 v225, v74, v75
	v_sub_f32_e32 v84, v84, v193
	v_sub_f32_e32 v85, v85, v193
	v_exp_f32_e32 v84, v84
	v_exp_f32_e32 v85, v85
	s_waitcnt lgkmcnt(14)
	v_mfma_f32_32x32x16_bf16 v[48:63], v[164:167], v[118:121], v[48:63]
	ds_read_b64_tr_b16 v[164:165], v213 offset:21568
	ds_read_b64_tr_b16 v[166:167], v213 offset:23104
	v_cvt_pk_bf16_f32 v226, v76, v77
	v_cvt_pk_bf16_f32 v227, v78, v79
	v_sub_f32_e32 v86, v86, v193
	v_sub_f32_e32 v87, v87, v193
	v_exp_f32_e32 v86, v86
	v_exp_f32_e32 v87, v87
	s_waitcnt lgkmcnt(14)
	v_mfma_f32_32x32x16_bf16 v[16:31], v[242:245], v[168:171], v[16:31]
	v_cvt_pk_bf16_f32 v246, v80, v81
	v_sub_f32_e32 v88, v88, v193
	v_sub_f32_e32 v89, v89, v193
	v_exp_f32_e32 v88, v88
	v_exp_f32_e32 v89, v89
	v_add_f32_e32 v216, v64, v66
	v_add_f32_e32 v217, v65, v67
	s_waitcnt lgkmcnt(12)
	v_mfma_f32_32x32x16_bf16 v[0:15], v[242:245], v[172:175], v[0:15]
	v_cvt_pk_bf16_f32 v247, v82, v83
	v_sub_f32_e32 v90, v90, v193
	v_sub_f32_e32 v91, v91, v193
	v_exp_f32_e32 v90, v90
	v_exp_f32_e32 v91, v91
	v_add_f32_e32 v216, v216, v68
	v_add_f32_e32 v217, v217, v69
	s_waitcnt lgkmcnt(10)
	v_mfma_f32_32x32x16_bf16 v[16:31], v[224:227], v[176:179], v[16:31]
	v_cvt_pk_bf16_f32 v248, v84, v85
	v_sub_f32_e32 v92, v92, v193
	v_sub_f32_e32 v93, v93, v193
	v_exp_f32_e32 v92, v92
	v_exp_f32_e32 v93, v93
	v_add_f32_e32 v216, v216, v70
	v_add_f32_e32 v217, v217, v71
	s_waitcnt lgkmcnt(8)
	v_mfma_f32_32x32x16_bf16 v[0:15], v[224:227], v[180:183], v[0:15]
	v_cvt_pk_bf16_f32 v249, v86, v87
	v_sub_f32_e32 v94, v94, v193
	v_sub_f32_e32 v95, v95, v193
	v_exp_f32_e32 v94, v94
	v_exp_f32_e32 v95, v95
	v_add_f32_e32 v216, v216, v72
	v_add_f32_e32 v217, v217, v73
	s_waitcnt lgkmcnt(6)
	v_mfma_f32_32x32x16_bf16 v[16:31], v[246:249], v[184:187], v[16:31]
	v_cvt_pk_bf16_f32 v242, v88, v89
	v_cvt_pk_bf16_f32 v243, v90, v91
	v_add_f32_e32 v216, v216, v74
	v_add_f32_e32 v217, v217, v75
	v_add_f32_e32 v216, v216, v76
	v_add_f32_e32 v217, v217, v77
	v_add_f32_e32 v216, v216, v78
	v_add_f32_e32 v217, v217, v79
	s_waitcnt lgkmcnt(4)
	v_mfma_f32_32x32x16_bf16 v[0:15], v[246:249], v[250:253], v[0:15]
	v_cvt_pk_bf16_f32 v244, v92, v93
	v_cvt_pk_bf16_f32 v245, v94, v95
	v_add_f32_e32 v216, v216, v80
	v_add_f32_e32 v217, v217, v81
	v_add_f32_e32 v216, v216, v82
	v_add_f32_e32 v217, v217, v83
	v_add_f32_e32 v216, v216, v84
	v_add_f32_e32 v217, v217, v85
	s_waitcnt lgkmcnt(2)
	v_mfma_f32_32x32x16_bf16 v[16:31], v[242:245], v[228:231], v[16:31]
	v_add_f32_e32 v216, v216, v86
	v_add_f32_e32 v217, v217, v87
	v_add_f32_e32 v216, v216, v88
	v_add_f32_e32 v217, v217, v89
	v_add_f32_e32 v216, v216, v90
	v_add_f32_e32 v217, v217, v91
	s_waitcnt lgkmcnt(0)
	v_mfma_f32_32x32x16_bf16 v[0:15], v[242:245], v[164:167], v[0:15]
	v_add_f32_e32 v216, v216, v92
	v_add_f32_e32 v217, v217, v93
	v_add_f32_e32 v216, v216, v94
	v_add_f32_e32 v217, v217, v95
	v_add_f32_e32 v216, v216, v217
	v_add_f32_e32 v191, v191, v216
